# v35: residual epilogue keeps 4-5 row groups of x loads in flight (4th staging slot + stored accumulators reused as staging)
# speedup vs baseline: 1.0008x; 1.0008x over previous
;   __device__ __forceinline__ void operator()(const f32x4 (&acc)[2][2][4][2], const Unit& u, int wr, int wc, int fr, int fq) const {
;     const int mr = (u.pm * 256 < ML) ? ((u.pm * 256) >> 11) : 32;
;     const float* gp = mod + (size_t)mr * 6144 + gate_off;
; #pragma unroll
;     for (int ai = 0; ai < 2; ++ai)
; #pragma unroll
;       for (int m = 0; m < 4; ++m) {
;         const int r = u.pm * 256 + ai * 128 + wr * 64 + m * 16 + fr;
;         const float* xi = (r < ML) ? xin_l + (size_t)r * 1024 : xin_c + (size_t)(r - ML) * 1024;
;         float* xo = (r < ML) ? xout_l + (size_t)r * 1024 : xout_c + (size_t)(r - ML) * 1024;
; #pragma unroll
;         for (int bj = 0; bj < 2; ++bj)
; #pragma unroll
;           for (int n = 0; n < 2; ++n) {
;             const int c = u.pn * 256 + bj * 128 + wc * 32 + n * 16 + 4 * fq;
;             const float4 g = *reinterpret_cast<const float4*>(gp + c);
;             const float4 x = *reinterpret_cast<const float4*>(xi + c);
;             const f32x4 v = acc[ai][bj][m][n];
;             *reinterpret_cast<float4*>(xo + c) = make_float4(x.x + g.x * v[0], x.y + g.y * v[1], x.z + g.z * v[2], x.w + g.w * v[3]);
;           }
;       }
;   }
.LBB0_1478:
	s_lshl_b64 s[18:19], s[18:19], 2
	s_add_u32 s18, s46, s18
	s_addc_u32 s19, s47, s19
	v_lshl_or_b32 v140, s49, 8, v144
	v_lshlrev_b32_e32 v140, 2, v140
	global_load_dwordx4 v[146:149], v140, s[18:19]
	global_load_dwordx4 v[150:153], v140, s[18:19] offset:64
	global_load_dwordx4 v[154:157], v140, s[18:19] offset:512
	global_load_dwordx4 v[158:161], v140, s[18:19] offset:576
	s_cmpk_lt_i32 s16, 0x100
	s_cselect_b32 s100, s41, s43
	s_cselect_b32 s101, s40, s42
	s_cselect_b32 s24, s74, s62
	s_cselect_b32 s25, s75, s63
	s_cselect_b32 s1, 0, 0x100
	s_sub_i32 s1, s16, s1
	s_lshl_b32 s1, s1, 20
	v_lshlrev_b32_e32 v141, 12, v1
	v_add3_u32 v141, v141, v140, s1
	global_load_dwordx4 v[162:165], v141, s[100:101]
	global_load_dwordx4 v[166:169], v141, s[100:101] offset:64
	global_load_dwordx4 v[170:173], v141, s[100:101] offset:512
	global_load_dwordx4 v[200:203], v141, s[100:101] offset:576
	v_add_u32_e32 v142, 0x10000, v141
	global_load_dwordx4 v[204:207], v142, s[100:101]
	global_load_dwordx4 v[208:211], v142, s[100:101] offset:64
	global_load_dwordx4 v[212:215], v142, s[100:101] offset:512
	global_load_dwordx4 v[216:219], v142, s[100:101] offset:576
	v_add_u32_e32 v143, 0x20000, v141
	global_load_dwordx4 v[220:223], v143, s[100:101]
	global_load_dwordx4 v[224:227], v143, s[100:101] offset:64
	global_load_dwordx4 v[228:231], v143, s[100:101] offset:512
	global_load_dwordx4 v[182:185], v143, s[100:101] offset:576
	v_add_u32_e32 v174, 0x30000, v141
	global_load_dwordx4 v[234:237], v174, s[100:101]
	global_load_dwordx4 v[238:241], v174, s[100:101] offset:64
	global_load_dwordx4 v[242:245], v174, s[100:101] offset:512
	global_load_dwordx4 v[246:249], v174, s[100:101] offset:576
	s_mov_b32 s49, s0
	s_mov_b32 s16, s10
	s_mov_b64 s[20:21], s[14:15]
	s_mov_b64 s[18:19], s[12:13]
	s_and_b64 vcc, exec, s[6:7]
	s_waitcnt vmcnt(12)
	v_pk_fma_f32 v[126:127], v[126:127], v[146:147], v[162:163]
	v_pk_fma_f32 v[128:129], v[128:129], v[148:149], v[164:165]
	v_pk_fma_f32 v[122:123], v[122:123], v[150:151], v[166:167]
	v_pk_fma_f32 v[124:125], v[124:125], v[152:153], v[168:169]
	v_pk_fma_f32 v[118:119], v[118:119], v[154:155], v[170:171]
	v_pk_fma_f32 v[120:121], v[120:121], v[156:157], v[172:173]
	v_pk_fma_f32 v[114:115], v[114:115], v[158:159], v[200:201]
	v_pk_fma_f32 v[116:117], v[116:117], v[160:161], v[202:203]
	global_store_dwordx4 v141, v[126:129], s[24:25]
	global_store_dwordx4 v141, v[122:125], s[24:25] offset:64
	global_store_dwordx4 v141, v[118:121], s[24:25] offset:512
	global_store_dwordx4 v141, v[114:117], s[24:25] offset:576
	v_add_u32_e32 v175, 0x80000, v141
	global_load_dwordx4 v[162:165], v175, s[100:101]
	global_load_dwordx4 v[166:169], v175, s[100:101] offset:64
	global_load_dwordx4 v[170:173], v175, s[100:101] offset:512
	global_load_dwordx4 v[200:203], v175, s[100:101] offset:576
	v_add_u32_e32 v232, 0x90000, v141
	global_load_dwordx4 v[126:129], v232, s[100:101]
	global_load_dwordx4 v[122:125], v232, s[100:101] offset:64
	global_load_dwordx4 v[118:121], v232, s[100:101] offset:512
	global_load_dwordx4 v[114:117], v232, s[100:101] offset:576
	s_waitcnt vmcnt(20)
	v_pk_fma_f32 v[110:111], v[110:111], v[146:147], v[204:205]
	v_pk_fma_f32 v[112:113], v[112:113], v[148:149], v[206:207]
	v_pk_fma_f32 v[106:107], v[106:107], v[150:151], v[208:209]
	v_pk_fma_f32 v[108:109], v[108:109], v[152:153], v[210:211]
	v_pk_fma_f32 v[102:103], v[102:103], v[154:155], v[212:213]
	v_pk_fma_f32 v[104:105], v[104:105], v[156:157], v[214:215]
	v_pk_fma_f32 v[98:99], v[98:99], v[158:159], v[216:217]
	v_pk_fma_f32 v[100:101], v[100:101], v[160:161], v[218:219]
	global_store_dwordx4 v142, v[110:113], s[24:25]
	global_store_dwordx4 v142, v[106:109], s[24:25] offset:64
	global_store_dwordx4 v142, v[102:105], s[24:25] offset:512
	global_store_dwordx4 v142, v[98:101], s[24:25] offset:576
	v_add_u32_e32 v233, 0xa0000, v141
	global_load_dwordx4 v[204:207], v233, s[100:101]
	global_load_dwordx4 v[208:211], v233, s[100:101] offset:64
	global_load_dwordx4 v[212:215], v233, s[100:101] offset:512
	global_load_dwordx4 v[216:219], v233, s[100:101] offset:576
	v_add_u32_e32 v142, 0xb0000, v141
	global_load_dwordx4 v[110:113], v142, s[100:101]
	global_load_dwordx4 v[106:109], v142, s[100:101] offset:64
	global_load_dwordx4 v[102:105], v142, s[100:101] offset:512
	global_load_dwordx4 v[98:101], v142, s[100:101] offset:576
	s_waitcnt vmcnt(28)
;   __device__ __forceinline__ void operator()(const f32x4 (&acc)[2][2][4][2], const Unit& u, int wr, int wc, int fr, int fq) const {
;     const int mr = (u.pm * 256 < ML) ? ((u.pm * 256) >> 11) : 32;
;     const float* gp = mod + (size_t)mr * 6144 + gate_off;
; #pragma unroll
;     for (int ai = 0; ai < 2; ++ai)
; #pragma unroll
;       for (int m = 0; m < 4; ++m) {
;         const int r = u.pm * 256 + ai * 128 + wr * 64 + m * 16 + fr;
;         const float* xi = (r < ML) ? xin_l + (size_t)r * 1024 : xin_c + (size_t)(r - ML) * 1024;
;         float* xo = (r < ML) ? xout_l + (size_t)r * 1024 : xout_c + (size_t)(r - ML) * 1024;
; #pragma unroll
;         for (int bj = 0; bj < 2; ++bj)
; #pragma unroll
;           for (int n = 0; n < 2; ++n) {
;             const int c = u.pn * 256 + bj * 128 + wc * 32 + n * 16 + 4 * fq;
;             const float4 g = *reinterpret_cast<const float4*>(gp + c);
;             const float4 x = *reinterpret_cast<const float4*>(xi + c);
;             const f32x4 v = acc[ai][bj][m][n];
;             *reinterpret_cast<float4*>(xo + c) = make_float4(x.x + g.x * v[0], x.y + g.y * v[1], x.z + g.z * v[2], x.w + g.w * v[3]);
;           }
;       }
;   }
	v_pk_fma_f32 v[94:95], v[94:95], v[146:147], v[220:221]
	v_pk_fma_f32 v[96:97], v[96:97], v[148:149], v[222:223]
	v_pk_fma_f32 v[90:91], v[90:91], v[150:151], v[224:225]
	v_pk_fma_f32 v[92:93], v[92:93], v[152:153], v[226:227]
	v_pk_fma_f32 v[86:87], v[86:87], v[154:155], v[228:229]
	v_pk_fma_f32 v[88:89], v[88:89], v[156:157], v[230:231]
	v_pk_fma_f32 v[82:83], v[82:83], v[158:159], v[182:183]
	v_pk_fma_f32 v[84:85], v[84:85], v[160:161], v[184:185]
	global_store_dwordx4 v143, v[94:97], s[24:25]
	global_store_dwordx4 v143, v[90:93], s[24:25] offset:64
	global_store_dwordx4 v143, v[86:89], s[24:25] offset:512
	global_store_dwordx4 v143, v[82:85], s[24:25] offset:576
	s_waitcnt vmcnt(28)
	v_pk_fma_f32 v[78:79], v[78:79], v[146:147], v[234:235]
	v_pk_fma_f32 v[80:81], v[80:81], v[148:149], v[236:237]
	v_pk_fma_f32 v[74:75], v[74:75], v[150:151], v[238:239]
	v_pk_fma_f32 v[76:77], v[76:77], v[152:153], v[240:241]
	v_pk_fma_f32 v[70:71], v[70:71], v[154:155], v[242:243]
	v_pk_fma_f32 v[72:73], v[72:73], v[156:157], v[244:245]
	v_pk_fma_f32 v[66:67], v[66:67], v[158:159], v[246:247]
	v_pk_fma_f32 v[68:69], v[68:69], v[160:161], v[248:249]
	global_store_dwordx4 v174, v[78:81], s[24:25]
	global_store_dwordx4 v174, v[74:77], s[24:25] offset:64
	global_store_dwordx4 v174, v[70:73], s[24:25] offset:512
	global_store_dwordx4 v174, v[66:69], s[24:25] offset:576
	s_waitcnt vmcnt(24)
	v_pk_fma_f32 v[62:63], v[62:63], v[146:147], v[162:163]
	v_pk_fma_f32 v[64:65], v[64:65], v[148:149], v[164:165]
	v_pk_fma_f32 v[58:59], v[58:59], v[150:151], v[166:167]
	v_pk_fma_f32 v[60:61], v[60:61], v[152:153], v[168:169]
	v_pk_fma_f32 v[54:55], v[54:55], v[154:155], v[170:171]
	v_pk_fma_f32 v[56:57], v[56:57], v[156:157], v[172:173]
	v_pk_fma_f32 v[50:51], v[50:51], v[158:159], v[200:201]
	v_pk_fma_f32 v[52:53], v[52:53], v[160:161], v[202:203]
	global_store_dwordx4 v175, v[62:65], s[24:25]
	global_store_dwordx4 v175, v[58:61], s[24:25] offset:64
	global_store_dwordx4 v175, v[54:57], s[24:25] offset:512
	global_store_dwordx4 v175, v[50:53], s[24:25] offset:576
	s_waitcnt vmcnt(24)
	v_pk_fma_f32 v[46:47], v[46:47], v[146:147], v[126:127]
	v_pk_fma_f32 v[48:49], v[48:49], v[148:149], v[128:129]
	v_pk_fma_f32 v[42:43], v[42:43], v[150:151], v[122:123]
	v_pk_fma_f32 v[44:45], v[44:45], v[152:153], v[124:125]
	v_pk_fma_f32 v[38:39], v[38:39], v[154:155], v[118:119]
	v_pk_fma_f32 v[40:41], v[40:41], v[156:157], v[120:121]
	v_pk_fma_f32 v[34:35], v[34:35], v[158:159], v[114:115]
	v_pk_fma_f32 v[36:37], v[36:37], v[160:161], v[116:117]
	global_store_dwordx4 v232, v[46:49], s[24:25]
	global_store_dwordx4 v232, v[42:45], s[24:25] offset:64
	global_store_dwordx4 v232, v[38:41], s[24:25] offset:512
	global_store_dwordx4 v232, v[34:37], s[24:25] offset:576
	s_waitcnt vmcnt(20)
	v_pk_fma_f32 v[30:31], v[30:31], v[146:147], v[204:205]
	v_pk_fma_f32 v[32:33], v[32:33], v[148:149], v[206:207]
	v_pk_fma_f32 v[26:27], v[26:27], v[150:151], v[208:209]
	v_pk_fma_f32 v[28:29], v[28:29], v[152:153], v[210:211]
	v_pk_fma_f32 v[22:23], v[22:23], v[154:155], v[212:213]
	v_pk_fma_f32 v[24:25], v[24:25], v[156:157], v[214:215]
	v_pk_fma_f32 v[18:19], v[18:19], v[158:159], v[216:217]
	v_pk_fma_f32 v[20:21], v[20:21], v[160:161], v[218:219]
	global_store_dwordx4 v233, v[30:33], s[24:25]
	global_store_dwordx4 v233, v[26:29], s[24:25] offset:64
	global_store_dwordx4 v233, v[22:25], s[24:25] offset:512
	global_store_dwordx4 v233, v[18:21], s[24:25] offset:576
	s_waitcnt vmcnt(20)
	v_pk_fma_f32 v[14:15], v[14:15], v[146:147], v[110:111]
	v_pk_fma_f32 v[16:17], v[16:17], v[148:149], v[112:113]
	v_pk_fma_f32 v[10:11], v[10:11], v[150:151], v[106:107]
	v_pk_fma_f32 v[12:13], v[12:13], v[152:153], v[108:109]
	v_pk_fma_f32 v[6:7], v[6:7], v[154:155], v[102:103]
	v_pk_fma_f32 v[8:9], v[8:9], v[156:157], v[104:105]
	v_pk_fma_f32 v[2:3], v[2:3], v[158:159], v[98:99]
	v_pk_fma_f32 v[4:5], v[4:5], v[160:161], v[100:101]
	global_store_dwordx4 v142, v[14:17], s[24:25]
	global_store_dwordx4 v142, v[10:13], s[24:25] offset:64
	global_store_dwordx4 v142, v[6:9], s[24:25] offset:512
	global_store_dwordx4 v142, v[2:5], s[24:25] offset:576
	s_cbranch_vccnz .LBB0_1485

;   __device__ __forceinline__ void operator()(const f32x4 (&acc)[2][2][4][2], const Unit& u, int wr, int wc, int fr, int fq) const {
;     const int mr = (u.pm * 256 < ML) ? ((u.pm * 256) >> 11) : 32;
;     const float* gp = mod + (size_t)mr * 6144 + gate_off;
; #pragma unroll
;     for (int ai = 0; ai < 2; ++ai)
; #pragma unroll
;       for (int m = 0; m < 4; ++m) {
;         const int r = u.pm * 256 + ai * 128 + wr * 64 + m * 16 + fr;
;         const float* xi = (r < ML) ? xin_l + (size_t)r * 1024 : xin_c + (size_t)(r - ML) * 1024;
;         float* xo = (r < ML) ? xout_l + (size_t)r * 1024 : xout_c + (size_t)(r - ML) * 1024;
; #pragma unroll
;         for (int bj = 0; bj < 2; ++bj)
; #pragma unroll
;           for (int n = 0; n < 2; ++n) {
;             const int c = u.pn * 256 + bj * 128 + wc * 32 + n * 16 + 4 * fq;
;             const float4 g = *reinterpret_cast<const float4*>(gp + c);
;             const float4 x = *reinterpret_cast<const float4*>(xi + c);
;             const f32x4 v = acc[ai][bj][m][n];
;             *reinterpret_cast<float4*>(xo + c) = make_float4(x.x + g.x * v[0], x.y + g.y * v[1], x.z + g.z * v[2], x.w + g.w * v[3]);
;           }
;       }
;   }
.LBB0_1665:
	s_lshl_b64 s[10:11], s[10:11], 2
	s_add_u32 s10, s30, s10
	s_addc_u32 s11, s31, s11
	v_lshl_or_b32 v140, s38, 8, v144
	v_lshlrev_b32_e32 v140, 2, v140
	global_load_dwordx4 v[146:149], v140, s[10:11]
	global_load_dwordx4 v[150:153], v140, s[10:11] offset:64
	global_load_dwordx4 v[154:157], v140, s[10:11] offset:512
	global_load_dwordx4 v[158:161], v140, s[10:11] offset:576
	s_cmpk_lt_i32 s37, 0x100
	s_cselect_b64 s[100:101], s[74:75], s[62:63]
	s_cselect_b32 s10, 0, 0x100
	s_sub_i32 s10, s37, s10
	s_lshl_b32 s10, s10, 20
	v_lshlrev_b32_e32 v141, 12, v1
	v_add3_u32 v141, v141, v140, s10
	global_load_dwordx4 v[162:165], v141, s[100:101]
	global_load_dwordx4 v[166:169], v141, s[100:101] offset:64
	global_load_dwordx4 v[170:173], v141, s[100:101] offset:512
	global_load_dwordx4 v[200:203], v141, s[100:101] offset:576
	v_add_u32_e32 v142, 0x10000, v141
	global_load_dwordx4 v[204:207], v142, s[100:101]
	global_load_dwordx4 v[208:211], v142, s[100:101] offset:64
	global_load_dwordx4 v[212:215], v142, s[100:101] offset:512
	global_load_dwordx4 v[216:219], v142, s[100:101] offset:576
	v_add_u32_e32 v143, 0x20000, v141
	global_load_dwordx4 v[220:223], v143, s[100:101]
	global_load_dwordx4 v[224:227], v143, s[100:101] offset:64
	global_load_dwordx4 v[228:231], v143, s[100:101] offset:512
	global_load_dwordx4 v[182:185], v143, s[100:101] offset:576
	v_add_u32_e32 v174, 0x30000, v141
	global_load_dwordx4 v[234:237], v174, s[100:101]
	global_load_dwordx4 v[238:241], v174, s[100:101] offset:64
	global_load_dwordx4 v[242:245], v174, s[100:101] offset:512
	global_load_dwordx4 v[246:249], v174, s[100:101] offset:576
	v_readlane_b32 s40, v253, 12
	v_readlane_b32 s41, v253, 13
	v_readlane_b32 s44, v253, 16
	v_readlane_b32 s45, v253, 17
	v_readlane_b32 s52, v253, 24
	v_readlane_b32 s53, v253, 25
	v_readlane_b32 s54, v253, 26
	v_readlane_b32 s55, v253, 27
	v_readlane_b32 s42, v253, 14
	v_readlane_b32 s43, v253, 15
	v_readlane_b32 s46, v253, 18
	v_readlane_b32 s47, v253, 19
	v_readlane_b32 s48, v253, 20
	v_readlane_b32 s49, v253, 21
	v_readlane_b32 s50, v253, 22
	v_readlane_b32 s51, v253, 23
	s_mov_b32 s38, s35
	s_mov_b32 s37, s36
	s_mov_b64 s[12:13], s[0:1]
	s_and_b64 vcc, exec, s[4:5]
	s_waitcnt vmcnt(12)
	v_pk_fma_f32 v[126:127], v[126:127], v[146:147], v[162:163]
	v_pk_fma_f32 v[128:129], v[128:129], v[148:149], v[164:165]
	v_pk_fma_f32 v[122:123], v[122:123], v[150:151], v[166:167]
	v_pk_fma_f32 v[124:125], v[124:125], v[152:153], v[168:169]
	v_pk_fma_f32 v[118:119], v[118:119], v[154:155], v[170:171]
	v_pk_fma_f32 v[120:121], v[120:121], v[156:157], v[172:173]
	v_pk_fma_f32 v[114:115], v[114:115], v[158:159], v[200:201]
	v_pk_fma_f32 v[116:117], v[116:117], v[160:161], v[202:203]
	global_store_dwordx4 v141, v[126:129], s[100:101]
	global_store_dwordx4 v141, v[122:125], s[100:101] offset:64
	global_store_dwordx4 v141, v[118:121], s[100:101] offset:512
	global_store_dwordx4 v141, v[114:117], s[100:101] offset:576
	v_add_u32_e32 v175, 0x80000, v141
	global_load_dwordx4 v[162:165], v175, s[100:101]
	global_load_dwordx4 v[166:169], v175, s[100:101] offset:64
	global_load_dwordx4 v[170:173], v175, s[100:101] offset:512
	global_load_dwordx4 v[200:203], v175, s[100:101] offset:576
	v_add_u32_e32 v232, 0x90000, v141
	global_load_dwordx4 v[126:129], v232, s[100:101]
	global_load_dwordx4 v[122:125], v232, s[100:101] offset:64
	global_load_dwordx4 v[118:121], v232, s[100:101] offset:512
	global_load_dwordx4 v[114:117], v232, s[100:101] offset:576
	s_waitcnt vmcnt(20)
	v_pk_fma_f32 v[110:111], v[110:111], v[146:147], v[204:205]
	v_pk_fma_f32 v[112:113], v[112:113], v[148:149], v[206:207]
	v_pk_fma_f32 v[106:107], v[106:107], v[150:151], v[208:209]
	v_pk_fma_f32 v[108:109], v[108:109], v[152:153], v[210:211]
	v_pk_fma_f32 v[102:103], v[102:103], v[154:155], v[212:213]
	v_pk_fma_f32 v[104:105], v[104:105], v[156:157], v[214:215]
	v_pk_fma_f32 v[98:99], v[98:99], v[158:159], v[216:217]
	v_pk_fma_f32 v[100:101], v[100:101], v[160:161], v[218:219]
	global_store_dwordx4 v142, v[110:113], s[100:101]
	global_store_dwordx4 v142, v[106:109], s[100:101] offset:64
	global_store_dwordx4 v142, v[102:105], s[100:101] offset:512
	global_store_dwordx4 v142, v[98:101], s[100:101] offset:576
	v_add_u32_e32 v233, 0xa0000, v141
	global_load_dwordx4 v[204:207], v233, s[100:101]
	global_load_dwordx4 v[208:211], v233, s[100:101] offset:64
	global_load_dwordx4 v[212:215], v233, s[100:101] offset:512
	global_load_dwordx4 v[216:219], v233, s[100:101] offset:576
	v_add_u32_e32 v142, 0xb0000, v141
	global_load_dwordx4 v[110:113], v142, s[100:101]
	global_load_dwordx4 v[106:109], v142, s[100:101] offset:64
	global_load_dwordx4 v[102:105], v142, s[100:101] offset:512
	global_load_dwordx4 v[98:101], v142, s[100:101] offset:576
	s_waitcnt vmcnt(28)
;   __device__ __forceinline__ void operator()(const f32x4 (&acc)[2][2][4][2], const Unit& u, int wr, int wc, int fr, int fq) const {
;     const int mr = (u.pm * 256 < ML) ? ((u.pm * 256) >> 11) : 32;
;     const float* gp = mod + (size_t)mr * 6144 + gate_off;
; #pragma unroll
;     for (int ai = 0; ai < 2; ++ai)
; #pragma unroll
;       for (int m = 0; m < 4; ++m) {
;         const int r = u.pm * 256 + ai * 128 + wr * 64 + m * 16 + fr;
;         const float* xi = (r < ML) ? xin_l + (size_t)r * 1024 : xin_c + (size_t)(r - ML) * 1024;
;         float* xo = (r < ML) ? xout_l + (size_t)r * 1024 : xout_c + (size_t)(r - ML) * 1024;
; #pragma unroll
;         for (int bj = 0; bj < 2; ++bj)
; #pragma unroll
;           for (int n = 0; n < 2; ++n) {
;             const int c = u.pn * 256 + bj * 128 + wc * 32 + n * 16 + 4 * fq;
;             const float4 g = *reinterpret_cast<const float4*>(gp + c);
;             const float4 x = *reinterpret_cast<const float4*>(xi + c);
;             const f32x4 v = acc[ai][bj][m][n];
;             *reinterpret_cast<float4*>(xo + c) = make_float4(x.x + g.x * v[0], x.y + g.y * v[1], x.z + g.z * v[2], x.w + g.w * v[3]);
;           }
;       }
;   }
	v_pk_fma_f32 v[94:95], v[94:95], v[146:147], v[220:221]
	v_pk_fma_f32 v[96:97], v[96:97], v[148:149], v[222:223]
	v_pk_fma_f32 v[90:91], v[90:91], v[150:151], v[224:225]
	v_pk_fma_f32 v[92:93], v[92:93], v[152:153], v[226:227]
	v_pk_fma_f32 v[86:87], v[86:87], v[154:155], v[228:229]
	v_pk_fma_f32 v[88:89], v[88:89], v[156:157], v[230:231]
	v_pk_fma_f32 v[82:83], v[82:83], v[158:159], v[182:183]
	v_pk_fma_f32 v[84:85], v[84:85], v[160:161], v[184:185]
	global_store_dwordx4 v143, v[94:97], s[100:101]
	global_store_dwordx4 v143, v[90:93], s[100:101] offset:64
	global_store_dwordx4 v143, v[86:89], s[100:101] offset:512
	global_store_dwordx4 v143, v[82:85], s[100:101] offset:576
	s_waitcnt vmcnt(28)
	v_pk_fma_f32 v[78:79], v[78:79], v[146:147], v[234:235]
	v_pk_fma_f32 v[80:81], v[80:81], v[148:149], v[236:237]
	v_pk_fma_f32 v[74:75], v[74:75], v[150:151], v[238:239]
	v_pk_fma_f32 v[76:77], v[76:77], v[152:153], v[240:241]
	v_pk_fma_f32 v[70:71], v[70:71], v[154:155], v[242:243]
	v_pk_fma_f32 v[72:73], v[72:73], v[156:157], v[244:245]
	v_pk_fma_f32 v[66:67], v[66:67], v[158:159], v[246:247]
	v_pk_fma_f32 v[68:69], v[68:69], v[160:161], v[248:249]
	global_store_dwordx4 v174, v[78:81], s[100:101]
	global_store_dwordx4 v174, v[74:77], s[100:101] offset:64
	global_store_dwordx4 v174, v[70:73], s[100:101] offset:512
	global_store_dwordx4 v174, v[66:69], s[100:101] offset:576
	s_waitcnt vmcnt(24)
	v_pk_fma_f32 v[62:63], v[62:63], v[146:147], v[162:163]
	v_pk_fma_f32 v[64:65], v[64:65], v[148:149], v[164:165]
	v_pk_fma_f32 v[58:59], v[58:59], v[150:151], v[166:167]
	v_pk_fma_f32 v[60:61], v[60:61], v[152:153], v[168:169]
	v_pk_fma_f32 v[54:55], v[54:55], v[154:155], v[170:171]
	v_pk_fma_f32 v[56:57], v[56:57], v[156:157], v[172:173]
	v_pk_fma_f32 v[50:51], v[50:51], v[158:159], v[200:201]
	v_pk_fma_f32 v[52:53], v[52:53], v[160:161], v[202:203]
	global_store_dwordx4 v175, v[62:65], s[100:101]
	global_store_dwordx4 v175, v[58:61], s[100:101] offset:64
	global_store_dwordx4 v175, v[54:57], s[100:101] offset:512
	global_store_dwordx4 v175, v[50:53], s[100:101] offset:576
	s_waitcnt vmcnt(24)
	v_pk_fma_f32 v[46:47], v[46:47], v[146:147], v[126:127]
	v_pk_fma_f32 v[48:49], v[48:49], v[148:149], v[128:129]
	v_pk_fma_f32 v[42:43], v[42:43], v[150:151], v[122:123]
	v_pk_fma_f32 v[44:45], v[44:45], v[152:153], v[124:125]
	v_pk_fma_f32 v[38:39], v[38:39], v[154:155], v[118:119]
	v_pk_fma_f32 v[40:41], v[40:41], v[156:157], v[120:121]
	v_pk_fma_f32 v[34:35], v[34:35], v[158:159], v[114:115]
	v_pk_fma_f32 v[36:37], v[36:37], v[160:161], v[116:117]
	global_store_dwordx4 v232, v[46:49], s[100:101]
	global_store_dwordx4 v232, v[42:45], s[100:101] offset:64
	global_store_dwordx4 v232, v[38:41], s[100:101] offset:512
	global_store_dwordx4 v232, v[34:37], s[100:101] offset:576
	s_waitcnt vmcnt(20)
	v_pk_fma_f32 v[30:31], v[30:31], v[146:147], v[204:205]
	v_pk_fma_f32 v[32:33], v[32:33], v[148:149], v[206:207]
	v_pk_fma_f32 v[26:27], v[26:27], v[150:151], v[208:209]
	v_pk_fma_f32 v[28:29], v[28:29], v[152:153], v[210:211]
	v_pk_fma_f32 v[22:23], v[22:23], v[154:155], v[212:213]
	v_pk_fma_f32 v[24:25], v[24:25], v[156:157], v[214:215]
	v_pk_fma_f32 v[18:19], v[18:19], v[158:159], v[216:217]
	v_pk_fma_f32 v[20:21], v[20:21], v[160:161], v[218:219]
	global_store_dwordx4 v233, v[30:33], s[100:101]
	global_store_dwordx4 v233, v[26:29], s[100:101] offset:64
	global_store_dwordx4 v233, v[22:25], s[100:101] offset:512
	global_store_dwordx4 v233, v[18:21], s[100:101] offset:576
	s_waitcnt vmcnt(20)
	v_pk_fma_f32 v[14:15], v[14:15], v[146:147], v[110:111]
	v_pk_fma_f32 v[16:17], v[16:17], v[148:149], v[112:113]
	v_pk_fma_f32 v[10:11], v[10:11], v[150:151], v[106:107]
	v_pk_fma_f32 v[12:13], v[12:13], v[152:153], v[108:109]
	v_pk_fma_f32 v[6:7], v[6:7], v[154:155], v[102:103]
	v_pk_fma_f32 v[8:9], v[8:9], v[156:157], v[104:105]
	v_pk_fma_f32 v[2:3], v[2:3], v[158:159], v[98:99]
	v_pk_fma_f32 v[4:5], v[4:5], v[160:161], v[100:101]
	global_store_dwordx4 v142, v[14:17], s[100:101]
	global_store_dwordx4 v142, v[10:13], s[100:101] offset:64
	global_store_dwordx4 v142, v[6:9], s[100:101] offset:512
	global_store_dwordx4 v142, v[2:5], s[100:101] offset:576
	s_mov_b64 s[10:11], s[6:7]
	s_cbranch_vccnz .LBB0_1676
